# non-temporal (nt) hint on the streaming f32 input reads: PEER table rows and x in the prologue, residual x in the out-projection epilogue
# speedup vs baseline: 1.0177x; 1.0007x over previous
; __device__ __forceinline__ unsigned cvt_pk_bf16(float lo, float hi) { unsigned r; asm volatile("v_cvt_pk_bf16_f32 %0, %1, %2" : "=v"(r) : "v"(lo), "v"(hi)); return r; }
;     __device__ __forceinline__ void operator()(const f32x4 (&acc)[2][2][4][2], const Unit& u, int wr, int wc, int fr, int fq) const {
; #pragma unroll
;         for (int ai = 0; ai < 2; ++ai)
; #pragma unroll
;             for (int m = 0; m < 4; ++m) {
;                 const int row = u.pm * BM + ai * HALF + wr * 64 + m * 16 + fr;
;                 const float* xr = xrow(xp, xs, row);
; #pragma unroll
;                 for (int bj = 0; bj < 2; ++bj) {
;                     const int col = u.pn * BM + bj * HALF + wc * 32 + 8 * fq;
;                     const f32x4 x0 = *(const f32x4*)(xr + col), x1v = *(const f32x4*)(xr + col + 4);
;                     const f32x4 v0 = acc[ai][bj][m][0] + x0, v1 = acc[ai][bj][m][1] + x1v;
;                     u32x4 w; w.x = cvt_pk_bf16(v0[0], v0[1]); w.y = cvt_pk_bf16(v0[2], v0[3]); w.z = cvt_pk_bf16(v1[0], v1[1]); w.w = cvt_pk_bf16(v1[2], v1[3]);
;                     *(u32x4*)(X1B + (size_t)row * D + col) = w;
;                 }
;             }
.LBB0_516:
	v_lshl_add_u32 v144, s26, 8, v150
	v_add_u32_e32 v148, 0xffffc000, v144
	v_ashrrev_i32_e32 v145, 31, v144
	v_cmp_gt_i32_e32 vcc, s41, v144
	v_lshl_or_b32 v146, s48, 8, v152
	v_mov_b32_e32 v156, s19
	v_cndmask_b32_e32 v149, 0, v145, vcc
	v_cndmask_b32_e32 v148, v148, v144, vcc
	v_mov_b32_e32 v157, s17
	v_mov_b32_e32 v158, s18
	v_mov_b32_e32 v159, s16
	v_ashrrev_i32_e32 v147, 31, v146
	v_cndmask_b32_e32 v161, v156, v157, vcc
	v_cndmask_b32_e32 v160, v158, v159, vcc
	v_lshlrev_b64 v[148:149], 12, v[148:149]
	v_lshl_add_u64 v[160:161], v[160:161], 0, v[148:149]
	v_lshlrev_b64 v[148:149], 2, v[146:147]
	v_lshl_add_u64 v[168:169], v[160:161], 0, v[148:149]
	global_load_dwordx4 v[160:163], v[168:169], off nt
	global_load_dwordx4 v[164:167], v[168:169], off offset:16 nt
	v_lshlrev_b64 v[170:171], 11, v[144:145]
	v_lshlrev_b64 v[146:147], 1, v[146:147]
	v_lshl_add_u64 v[170:171], s[20:21], 0, v[170:171]
	v_lshl_add_u64 v[170:171], v[170:171], 0, v[146:147]
	v_add_u32_e32 v145, 0xffffc010, v144
	s_waitcnt vmcnt(0)
	v_pk_add_f32 v[124:125], v[124:125], v[160:161]
	v_pk_add_f32 v[160:161], v[122:123], v[166:167]
	v_pk_add_f32 v[122:123], v[120:121], v[164:165]
	v_pk_add_f32 v[126:127], v[126:127], v[162:163]
	v_cvt_pk_bf16_f32 v120, v124, v125
	s_nop 0
	v_cvt_pk_bf16_f32 v121, v126, v127
	v_cvt_pk_bf16_f32 v122, v122, v123
	v_cvt_pk_bf16_f32 v123, v160, v161
	global_store_dwordx4 v[170:171], v[120:123], off
	global_load_dwordx4 v[120:123], v[168:169], off offset:512 nt
	s_nop 0
	global_load_dwordx4 v[124:127], v[168:169], off offset:528 nt
	v_or_b32_e32 v160, 16, v144
	v_ashrrev_i32_e32 v161, 31, v160
	v_cmp_gt_i32_e32 vcc, s41, v160
	s_waitcnt vmcnt(1)
	v_pk_add_f32 v[116:117], v[116:117], v[120:121]
	v_cndmask_b32_e32 v163, 0, v161, vcc
	v_cndmask_b32_e32 v162, v145, v160, vcc
	v_cndmask_b32_e32 v165, v156, v157, vcc
	v_cndmask_b32_e32 v164, v158, v159, vcc
	v_lshlrev_b64 v[162:163], 12, v[162:163]
	v_lshl_add_u64 v[162:163], v[164:165], 0, v[162:163]
	s_waitcnt vmcnt(0)
	v_pk_add_f32 v[120:121], v[114:115], v[126:127]
	v_pk_add_f32 v[114:115], v[112:113], v[124:125]
	v_lshl_add_u64 v[162:163], v[162:163], 0, v[148:149]
	v_pk_add_f32 v[118:119], v[118:119], v[122:123]
	v_cvt_pk_bf16_f32 v112, v116, v117
	s_nop 0
	v_cvt_pk_bf16_f32 v113, v118, v119
	v_cvt_pk_bf16_f32 v114, v114, v115
	v_cvt_pk_bf16_f32 v115, v120, v121
	global_store_dwordx4 v[170:171], v[112:115], off offset:256
	global_load_dwordx4 v[112:115], v[162:163], off nt
	s_nop 0
	global_load_dwordx4 v[116:119], v[162:163], off offset:16 nt
	v_lshlrev_b64 v[120:121], 11, v[160:161]
	v_lshl_add_u64 v[120:121], s[20:21], 0, v[120:121]
	v_lshl_add_u64 v[120:121], v[120:121], 0, v[146:147]
	s_waitcnt vmcnt(1)
	v_pk_add_f32 v[108:109], v[108:109], v[112:113]
	s_waitcnt vmcnt(0)
	v_pk_add_f32 v[112:113], v[106:107], v[118:119]
	v_pk_add_f32 v[106:107], v[104:105], v[116:117]
	v_pk_add_f32 v[110:111], v[110:111], v[114:115]
	v_cvt_pk_bf16_f32 v104, v108, v109
	v_add_u32_e32 v114, 0xffffc020, v144
	v_cvt_pk_bf16_f32 v105, v110, v111
	v_cvt_pk_bf16_f32 v106, v106, v107
	v_cvt_pk_bf16_f32 v107, v112, v113
	global_store_dwordx4 v[120:121], v[104:107], off
	global_load_dwordx4 v[104:107], v[162:163], off offset:512 nt
	s_nop 0
	global_load_dwordx4 v[108:111], v[162:163], off offset:528 nt
	v_or_b32_e32 v112, 32, v144
	v_ashrrev_i32_e32 v113, 31, v112
	v_cmp_gt_i32_e32 vcc, s41, v112
	s_waitcnt vmcnt(1)
	v_pk_add_f32 v[100:101], v[100:101], v[104:105]
	v_cndmask_b32_e32 v115, 0, v113, vcc
	v_cndmask_b32_e32 v114, v114, v112, vcc
	v_cndmask_b32_e32 v117, v156, v157, vcc
	v_cndmask_b32_e32 v116, v158, v159, vcc
	v_lshlrev_b64 v[114:115], 12, v[114:115]
	v_lshl_add_u64 v[114:115], v[116:117], 0, v[114:115]
	s_waitcnt vmcnt(0)
	v_pk_add_f32 v[104:105], v[98:99], v[110:111]
	v_pk_add_f32 v[98:99], v[96:97], v[108:109]
	v_lshl_add_u64 v[114:115], v[114:115], 0, v[148:149]
	v_pk_add_f32 v[102:103], v[102:103], v[106:107]
	v_cvt_pk_bf16_f32 v96, v100, v101
	s_nop 0
	v_cvt_pk_bf16_f32 v97, v102, v103
	v_cvt_pk_bf16_f32 v98, v98, v99
	v_cvt_pk_bf16_f32 v99, v104, v105
	global_store_dwordx4 v[120:121], v[96:99], off offset:256
	global_load_dwordx4 v[96:99], v[114:115], off nt
	s_nop 0
	global_load_dwordx4 v[100:103], v[114:115], off offset:16 nt
	v_lshlrev_b64 v[104:105], 11, v[112:113]
	v_lshl_add_u64 v[104:105], s[20:21], 0, v[104:105]
	v_lshl_add_u64 v[104:105], v[104:105], 0, v[146:147]
	s_waitcnt vmcnt(1)
	v_pk_add_f32 v[92:93], v[92:93], v[96:97]
	s_waitcnt vmcnt(0)
	v_pk_add_f32 v[96:97], v[90:91], v[102:103]
	v_pk_add_f32 v[90:91], v[88:89], v[100:101]
	v_pk_add_f32 v[94:95], v[94:95], v[98:99]
	v_cvt_pk_bf16_f32 v88, v92, v93
	v_add_u32_e32 v98, 0xffffc030, v144
	v_cvt_pk_bf16_f32 v89, v94, v95
	v_cvt_pk_bf16_f32 v90, v90, v91
	v_cvt_pk_bf16_f32 v91, v96, v97
	global_store_dwordx4 v[104:105], v[88:91], off
	global_load_dwordx4 v[88:91], v[114:115], off offset:512 nt
	s_nop 0
	global_load_dwordx4 v[92:95], v[114:115], off offset:528 nt
	v_or_b32_e32 v96, 48, v144
	v_ashrrev_i32_e32 v97, 31, v96
	v_cmp_gt_i32_e32 vcc, s41, v96
	s_waitcnt vmcnt(1)
	v_pk_add_f32 v[84:85], v[84:85], v[88:89]
	v_cndmask_b32_e32 v99, 0, v97, vcc
	v_cndmask_b32_e32 v98, v98, v96, vcc
	v_cndmask_b32_e32 v101, v156, v157, vcc
	v_cndmask_b32_e32 v100, v158, v159, vcc
	v_lshlrev_b64 v[98:99], 12, v[98:99]
	v_lshl_add_u64 v[98:99], v[100:101], 0, v[98:99]
	s_waitcnt vmcnt(0)
; __device__ __forceinline__ unsigned cvt_pk_bf16(float lo, float hi) { unsigned r; asm volatile("v_cvt_pk_bf16_f32 %0, %1, %2" : "=v"(r) : "v"(lo), "v"(hi)); return r; }
;     __device__ __forceinline__ void operator()(const f32x4 (&acc)[2][2][4][2], const Unit& u, int wr, int wc, int fr, int fq) const {
; #pragma unroll
;         for (int ai = 0; ai < 2; ++ai)
; #pragma unroll
;             for (int m = 0; m < 4; ++m) {
;                 const int row = u.pm * BM + ai * HALF + wr * 64 + m * 16 + fr;
;                 const float* xr = xrow(xp, xs, row);
; #pragma unroll
;                 for (int bj = 0; bj < 2; ++bj) {
;                     const int col = u.pn * BM + bj * HALF + wc * 32 + 8 * fq;
;                     const f32x4 x0 = *(const f32x4*)(xr + col), x1v = *(const f32x4*)(xr + col + 4);
;                     const f32x4 v0 = acc[ai][bj][m][0] + x0, v1 = acc[ai][bj][m][1] + x1v;
;                     u32x4 w; w.x = cvt_pk_bf16(v0[0], v0[1]); w.y = cvt_pk_bf16(v0[2], v0[3]); w.z = cvt_pk_bf16(v1[0], v1[1]); w.w = cvt_pk_bf16(v1[2], v1[3]);
;                     *(u32x4*)(X1B + (size_t)row * D + col) = w;
;                 }
;             }
	v_pk_add_f32 v[88:89], v[82:83], v[94:95]
	v_pk_add_f32 v[82:83], v[80:81], v[92:93]
	v_lshl_add_u64 v[98:99], v[98:99], 0, v[148:149]
	v_pk_add_f32 v[86:87], v[86:87], v[90:91]
	v_cvt_pk_bf16_f32 v80, v84, v85
	s_nop 0
	v_cvt_pk_bf16_f32 v81, v86, v87
	v_cvt_pk_bf16_f32 v82, v82, v83
	v_cvt_pk_bf16_f32 v83, v88, v89
	global_store_dwordx4 v[104:105], v[80:83], off offset:256
	global_load_dwordx4 v[80:83], v[98:99], off nt
	s_nop 0
	global_load_dwordx4 v[84:87], v[98:99], off offset:16 nt
	v_lshlrev_b64 v[88:89], 11, v[96:97]
	v_lshl_add_u64 v[88:89], s[20:21], 0, v[88:89]
	v_lshl_add_u64 v[88:89], v[88:89], 0, v[146:147]
	s_waitcnt vmcnt(1)
	v_pk_add_f32 v[76:77], v[76:77], v[80:81]
	s_waitcnt vmcnt(0)
	v_pk_add_f32 v[80:81], v[74:75], v[86:87]
	v_pk_add_f32 v[74:75], v[72:73], v[84:85]
	v_pk_add_f32 v[78:79], v[78:79], v[82:83]
	v_cvt_pk_bf16_f32 v72, v76, v77
	v_add_u32_e32 v82, 0xffffc080, v144
	v_cvt_pk_bf16_f32 v73, v78, v79
	v_cvt_pk_bf16_f32 v74, v74, v75
	v_cvt_pk_bf16_f32 v75, v80, v81
	global_store_dwordx4 v[88:89], v[72:75], off
	global_load_dwordx4 v[72:75], v[98:99], off offset:512 nt
	s_nop 0
	global_load_dwordx4 v[76:79], v[98:99], off offset:528 nt
	v_add_u32_e32 v80, 0x80, v144
	v_ashrrev_i32_e32 v81, 31, v80
	v_cmp_gt_i32_e32 vcc, s41, v80
	s_waitcnt vmcnt(1)
	v_pk_add_f32 v[68:69], v[68:69], v[72:73]
	v_cndmask_b32_e32 v83, 0, v81, vcc
	v_cndmask_b32_e32 v82, v82, v80, vcc
	v_cndmask_b32_e32 v85, v156, v157, vcc
	v_cndmask_b32_e32 v84, v158, v159, vcc
	v_lshlrev_b64 v[82:83], 12, v[82:83]
	v_lshl_add_u64 v[82:83], v[84:85], 0, v[82:83]
	s_waitcnt vmcnt(0)
	v_pk_add_f32 v[72:73], v[66:67], v[78:79]
	v_pk_add_f32 v[66:67], v[64:65], v[76:77]
	v_lshl_add_u64 v[82:83], v[82:83], 0, v[148:149]
	v_pk_add_f32 v[70:71], v[70:71], v[74:75]
	v_cvt_pk_bf16_f32 v64, v68, v69
	s_nop 0
	v_cvt_pk_bf16_f32 v65, v70, v71
	v_cvt_pk_bf16_f32 v66, v66, v67
	v_cvt_pk_bf16_f32 v67, v72, v73
	global_store_dwordx4 v[88:89], v[64:67], off offset:256
	global_load_dwordx4 v[64:67], v[82:83], off nt
	s_nop 0
	global_load_dwordx4 v[68:71], v[82:83], off offset:16 nt
	v_lshlrev_b64 v[72:73], 11, v[80:81]
	v_lshl_add_u64 v[72:73], s[20:21], 0, v[72:73]
	v_lshl_add_u64 v[72:73], v[72:73], 0, v[146:147]
	s_waitcnt vmcnt(1)
	v_pk_add_f32 v[60:61], v[60:61], v[64:65]
	s_waitcnt vmcnt(0)
	v_pk_add_f32 v[64:65], v[58:59], v[70:71]
	v_pk_add_f32 v[58:59], v[56:57], v[68:69]
	v_pk_add_f32 v[62:63], v[62:63], v[66:67]
	v_cvt_pk_bf16_f32 v56, v60, v61
	v_add_u32_e32 v66, 0xffffc090, v144
	v_cvt_pk_bf16_f32 v57, v62, v63
	v_cvt_pk_bf16_f32 v58, v58, v59
	v_cvt_pk_bf16_f32 v59, v64, v65
	global_store_dwordx4 v[72:73], v[56:59], off
	global_load_dwordx4 v[56:59], v[82:83], off offset:512 nt
	s_nop 0
	global_load_dwordx4 v[60:63], v[82:83], off offset:528 nt
	v_add_u32_e32 v64, 0x90, v144
	v_ashrrev_i32_e32 v65, 31, v64
	v_cmp_gt_i32_e32 vcc, s41, v64
	s_waitcnt vmcnt(1)
	v_pk_add_f32 v[52:53], v[52:53], v[56:57]
	v_cndmask_b32_e32 v67, 0, v65, vcc
	v_cndmask_b32_e32 v66, v66, v64, vcc
	v_cndmask_b32_e32 v69, v156, v157, vcc
	v_cndmask_b32_e32 v68, v158, v159, vcc
	v_lshlrev_b64 v[66:67], 12, v[66:67]
	v_lshl_add_u64 v[66:67], v[68:69], 0, v[66:67]
	s_waitcnt vmcnt(0)
	v_pk_add_f32 v[56:57], v[50:51], v[62:63]
	v_pk_add_f32 v[50:51], v[48:49], v[60:61]
	v_lshl_add_u64 v[66:67], v[66:67], 0, v[148:149]
	v_pk_add_f32 v[54:55], v[54:55], v[58:59]
	v_cvt_pk_bf16_f32 v48, v52, v53
	s_nop 0
	v_cvt_pk_bf16_f32 v49, v54, v55
	v_cvt_pk_bf16_f32 v50, v50, v51
	v_cvt_pk_bf16_f32 v51, v56, v57
	global_store_dwordx4 v[72:73], v[48:51], off offset:256
	global_load_dwordx4 v[48:51], v[66:67], off nt
	s_nop 0
	global_load_dwordx4 v[52:55], v[66:67], off offset:16 nt
	v_lshlrev_b64 v[56:57], 11, v[64:65]
	v_lshl_add_u64 v[56:57], s[20:21], 0, v[56:57]
	v_lshl_add_u64 v[56:57], v[56:57], 0, v[146:147]
	s_waitcnt vmcnt(1)
	v_pk_add_f32 v[44:45], v[44:45], v[48:49]
	s_waitcnt vmcnt(0)
; __device__ __forceinline__ unsigned cvt_pk_bf16(float lo, float hi) { unsigned r; asm volatile("v_cvt_pk_bf16_f32 %0, %1, %2" : "=v"(r) : "v"(lo), "v"(hi)); return r; }
;     __device__ __forceinline__ void operator()(const f32x4 (&acc)[2][2][4][2], const Unit& u, int wr, int wc, int fr, int fq) const {
; #pragma unroll
;         for (int ai = 0; ai < 2; ++ai)
; #pragma unroll
;             for (int m = 0; m < 4; ++m) {
;                 const int row = u.pm * BM + ai * HALF + wr * 64 + m * 16 + fr;
;                 const float* xr = xrow(xp, xs, row);
; #pragma unroll
;                 for (int bj = 0; bj < 2; ++bj) {
;                     const int col = u.pn * BM + bj * HALF + wc * 32 + 8 * fq;
;                     const f32x4 x0 = *(const f32x4*)(xr + col), x1v = *(const f32x4*)(xr + col + 4);
;                     const f32x4 v0 = acc[ai][bj][m][0] + x0, v1 = acc[ai][bj][m][1] + x1v;
;                     u32x4 w; w.x = cvt_pk_bf16(v0[0], v0[1]); w.y = cvt_pk_bf16(v0[2], v0[3]); w.z = cvt_pk_bf16(v1[0], v1[1]); w.w = cvt_pk_bf16(v1[2], v1[3]);
;                     *(u32x4*)(X1B + (size_t)row * D + col) = w;
;                 }
;             }
	v_pk_add_f32 v[48:49], v[42:43], v[54:55]
	v_pk_add_f32 v[42:43], v[40:41], v[52:53]
	v_pk_add_f32 v[46:47], v[46:47], v[50:51]
	v_cvt_pk_bf16_f32 v40, v44, v45
	v_add_u32_e32 v50, 0xffffc0a0, v144
	v_cvt_pk_bf16_f32 v41, v46, v47
	v_cvt_pk_bf16_f32 v42, v42, v43
	v_cvt_pk_bf16_f32 v43, v48, v49
	global_store_dwordx4 v[56:57], v[40:43], off
	global_load_dwordx4 v[40:43], v[66:67], off offset:512 nt
	s_nop 0
	global_load_dwordx4 v[44:47], v[66:67], off offset:528 nt
	v_add_u32_e32 v48, 0xa0, v144
	v_ashrrev_i32_e32 v49, 31, v48
	v_cmp_gt_i32_e32 vcc, s41, v48
	s_waitcnt vmcnt(1)
	v_pk_add_f32 v[36:37], v[36:37], v[40:41]
	v_cndmask_b32_e32 v51, 0, v49, vcc
	v_cndmask_b32_e32 v50, v50, v48, vcc
	v_cndmask_b32_e32 v53, v156, v157, vcc
	v_cndmask_b32_e32 v52, v158, v159, vcc
	v_lshlrev_b64 v[50:51], 12, v[50:51]
	v_lshl_add_u64 v[50:51], v[52:53], 0, v[50:51]
	s_waitcnt vmcnt(0)
	v_pk_add_f32 v[40:41], v[34:35], v[46:47]
	v_pk_add_f32 v[34:35], v[32:33], v[44:45]
	v_lshl_add_u64 v[50:51], v[50:51], 0, v[148:149]
	v_pk_add_f32 v[38:39], v[38:39], v[42:43]
	v_cvt_pk_bf16_f32 v32, v36, v37
	s_nop 0
	v_cvt_pk_bf16_f32 v33, v38, v39
	v_cvt_pk_bf16_f32 v34, v34, v35
	v_cvt_pk_bf16_f32 v35, v40, v41
	global_store_dwordx4 v[56:57], v[32:35], off offset:256
	global_load_dwordx4 v[32:35], v[50:51], off nt
	s_nop 0
	global_load_dwordx4 v[36:39], v[50:51], off offset:16 nt
	v_lshlrev_b64 v[40:41], 11, v[48:49]
	v_lshl_add_u64 v[40:41], s[20:21], 0, v[40:41]
	v_lshl_add_u64 v[40:41], v[40:41], 0, v[146:147]
	s_waitcnt vmcnt(1)
	v_pk_add_f32 v[28:29], v[28:29], v[32:33]
	s_waitcnt vmcnt(0)
	v_pk_add_f32 v[32:33], v[26:27], v[38:39]
	v_pk_add_f32 v[26:27], v[24:25], v[36:37]
	v_pk_add_f32 v[30:31], v[30:31], v[34:35]
	v_cvt_pk_bf16_f32 v24, v28, v29
	v_add_u32_e32 v34, 0xffffc0b0, v144
	v_cvt_pk_bf16_f32 v25, v30, v31
	v_cvt_pk_bf16_f32 v26, v26, v27
	v_cvt_pk_bf16_f32 v27, v32, v33
	global_store_dwordx4 v[40:41], v[24:27], off
	global_load_dwordx4 v[24:27], v[50:51], off offset:512 nt
	s_nop 0
	global_load_dwordx4 v[28:31], v[50:51], off offset:528 nt
	v_add_u32_e32 v32, 0xb0, v144
	v_ashrrev_i32_e32 v33, 31, v32
	v_cmp_gt_i32_e32 vcc, s41, v32
	s_waitcnt vmcnt(1)
	v_pk_add_f32 v[20:21], v[20:21], v[24:25]
	v_cndmask_b32_e32 v35, 0, v33, vcc
	v_cndmask_b32_e32 v34, v34, v32, vcc
	v_cndmask_b32_e32 v37, v156, v157, vcc
	v_cndmask_b32_e32 v36, v158, v159, vcc
	v_lshlrev_b64 v[34:35], 12, v[34:35]
	v_lshl_add_u64 v[34:35], v[36:37], 0, v[34:35]
	s_waitcnt vmcnt(0)
	v_pk_add_f32 v[24:25], v[18:19], v[30:31]
	v_pk_add_f32 v[18:19], v[16:17], v[28:29]
	v_lshl_add_u64 v[34:35], v[34:35], 0, v[148:149]
	v_pk_add_f32 v[22:23], v[22:23], v[26:27]
	v_cvt_pk_bf16_f32 v16, v20, v21
	s_andn2_b64 vcc, exec, s[0:1]
	v_cvt_pk_bf16_f32 v17, v22, v23
	v_cvt_pk_bf16_f32 v18, v18, v19
	v_cvt_pk_bf16_f32 v19, v24, v25
	global_store_dwordx4 v[40:41], v[16:19], off offset:256
	global_load_dwordx4 v[16:19], v[34:35], off nt
	s_nop 0
	global_load_dwordx4 v[20:23], v[34:35], off offset:16 nt
	v_lshlrev_b64 v[24:25], 11, v[32:33]
	v_lshl_add_u64 v[24:25], s[20:21], 0, v[24:25]
	v_lshl_add_u64 v[24:25], v[24:25], 0, v[146:147]
	s_mov_b64 s[0:1], -1
	s_waitcnt vmcnt(1)
	v_pk_add_f32 v[12:13], v[12:13], v[16:17]
	s_waitcnt vmcnt(0)
	v_pk_add_f32 v[16:17], v[10:11], v[22:23]
	v_pk_add_f32 v[10:11], v[8:9], v[20:21]
	v_pk_add_f32 v[14:15], v[14:15], v[18:19]
	v_cvt_pk_bf16_f32 v8, v12, v13
	s_nop 0
	v_cvt_pk_bf16_f32 v9, v14, v15
	v_cvt_pk_bf16_f32 v10, v10, v11
	v_cvt_pk_bf16_f32 v11, v16, v17
	global_store_dwordx4 v[24:25], v[8:11], off
	global_load_dwordx4 v[8:11], v[34:35], off offset:512 nt
	s_nop 0
	global_load_dwordx4 v[12:15], v[34:35], off offset:528 nt
	s_waitcnt vmcnt(1)
	v_pk_add_f32 v[4:5], v[4:5], v[8:9]
	s_waitcnt vmcnt(0)
	v_pk_add_f32 v[8:9], v[2:3], v[14:15]
	v_pk_add_f32 v[2:3], v[0:1], v[12:13]
	v_pk_add_f32 v[6:7], v[6:7], v[10:11]
	v_cvt_pk_bf16_f32 v0, v4, v5
	s_nop 0
	v_cvt_pk_bf16_f32 v1, v6, v7
	v_cvt_pk_bf16_f32 v2, v2, v3
	v_cvt_pk_bf16_f32 v3, v8, v9
	global_store_dwordx4 v[24:25], v[0:3], off offset:256
	s_cbranch_vccnz .LBB0_509
	s_andn2_b64 vcc, exec, s[4:5]
	s_cbranch_vccnz .LBB0_508
	s_barrier
	s_branch .LBB0_508
